# attention interior steps: probabilities exponentiated out of place, rescale guard on the lane partial row sum (>64) so the max chain leaves the common path
# speedup vs baseline: 1.0061x; 1.0061x over previous
; template <int CGM>
; __device__ __forceinline__ void step_int(const bf16x8 (&kf)[4][2], const bf16x8 (&q)[2][2], float farb, const bool (&selq)[2],
;                                          float (&m)[2], float (&l)[2], f32x4 (&o)[2][4], const unsigned char* Vs, int r, int fq) {
;     f32x4 s[2][4]; float mx[2] = {-1e30f, -1e30f};
; #pragma unroll
;     for (int cg_ = 0; cg_ < 2; ++cg_) if ((CGM >> cg_) & 1) { qk(s[cg_], kf, q[cg_], selq[cg_] ? farb - m[cg_] : -1e30f); mx[cg_] = red_max4(max16v(s[cg_])); }
;     if (__any(mx[0] > 0.f || mx[1] > 0.f)) {
; #pragma unroll
;         for (int cg_ = 0; cg_ < 2; ++cg_) if ((CGM >> cg_) & 1) {
;             const float d = fmaxf(mx[cg_], 0.f), sc = __builtin_amdgcn_exp2f(-d); m[cg_] += d; l[cg_] *= sc;
; #pragma unroll
;             for (int df = 0; df < 4; ++df) o[cg_][df] *= sc;
; #pragma unroll
;             for (int f = 0; f < 4; ++f) s[cg_][f] -= d;
;         }
;     }
;     float p[2][4][4];
; #pragma unroll
;     for (int cg_ = 0; cg_ < 2; ++cg_) if ((CGM >> cg_) & 1) {
;         float rs = 0.f;
; #pragma unroll
;         for (int f = 0; f < 4; ++f)
; #pragma unroll
;             for (int i = 0; i < 4; ++i) { const float pe = __builtin_amdgcn_exp2f(s[cg_][f][i]); p[cg_][f][i] = pe; rs += pe; }
;         l[cg_] += rs;
;     }
;     pv2<CGM>(o, p, Vs, r, fq);
; }
.Lsel_c3_e0:
	v_exp_f32_e32 v232, v92
	v_exp_f32_e32 v233, v93
	v_exp_f32_e32 v234, v94
	v_exp_f32_e32 v235, v95
	v_exp_f32_e32 v236, v96
	v_exp_f32_e32 v237, v97
	v_exp_f32_e32 v238, v98
	v_exp_f32_e32 v239, v99
	ds_read_b128 v[84:87], v142 offset:8192
	ds_read_b128 v[76:79], v142 offset:8704
	ds_read_b128 v[68:71], v142 offset:12288
	ds_read_b128 v[64:67], v142 offset:12800
	v_exp_f32_e32 v240, v100
	v_exp_f32_e32 v241, v101
	v_exp_f32_e32 v242, v102
	v_exp_f32_e32 v243, v103
	v_exp_f32_e32 v244, v104
	v_exp_f32_e32 v245, v105
	v_exp_f32_e32 v246, v106
	v_exp_f32_e32 v247, v107
	v_pk_add_f32 v[130:131], v[232:233], v[234:235]
	v_pk_add_f32 v[130:131], v[130:131], v[236:237]
	v_pk_add_f32 v[130:131], v[130:131], v[238:239]
	v_pk_add_f32 v[130:131], v[130:131], v[240:241]
	v_pk_add_f32 v[130:131], v[130:131], v[242:243]
	v_pk_add_f32 v[130:131], v[130:131], v[244:245]
	v_pk_add_f32 v[130:131], v[130:131], v[246:247]
	v_add_f32_e32 v130, v130, v131
	v_cmp_lt_f32_e32 vcc, 0x42800000, v130
	s_cbranch_vccnz .Lsel_c3_s0
	v_add_f32_e32 v127, v127, v130
	v_cvt_pk_bf16_f32 v92, v232, v233
	v_cvt_pk_bf16_f32 v93, v234, v235
	v_cvt_pk_bf16_f32 v94, v236, v237
	v_cvt_pk_bf16_f32 v95, v238, v239
	v_cvt_pk_bf16_f32 v96, v240, v241
	v_cvt_pk_bf16_f32 v97, v242, v243
	v_cvt_pk_bf16_f32 v98, v244, v245
	v_cvt_pk_bf16_f32 v99, v246, v247
.Lsel_c3_e1:
	v_exp_f32_e32 v232, v108
	v_exp_f32_e32 v233, v109
	v_exp_f32_e32 v234, v110
	v_exp_f32_e32 v235, v111
	v_exp_f32_e32 v236, v112
	v_exp_f32_e32 v237, v113
	v_exp_f32_e32 v238, v114
	v_exp_f32_e32 v239, v115
	v_exp_f32_e32 v240, v116
	v_exp_f32_e32 v241, v117
	v_exp_f32_e32 v242, v118
	v_exp_f32_e32 v243, v119
	v_exp_f32_e32 v244, v120
	v_exp_f32_e32 v245, v121
	v_exp_f32_e32 v246, v122
	v_exp_f32_e32 v247, v123
	v_pk_add_f32 v[146:147], v[232:233], v[234:235]
	v_pk_add_f32 v[146:147], v[146:147], v[236:237]
	v_pk_add_f32 v[146:147], v[146:147], v[238:239]
	v_pk_add_f32 v[146:147], v[146:147], v[240:241]
	v_pk_add_f32 v[146:147], v[146:147], v[242:243]
	v_pk_add_f32 v[146:147], v[146:147], v[244:245]
	v_pk_add_f32 v[146:147], v[146:147], v[246:247]
	v_add_f32_e32 v146, v146, v147
	v_cmp_lt_f32_e32 vcc, 0x42800000, v146
	s_cbranch_vccnz .Lsel_c3_s1
	v_add_f32_e32 v126, v126, v146
	v_cvt_pk_bf16_f32 v108, v232, v233
	v_cvt_pk_bf16_f32 v109, v234, v235
	v_cvt_pk_bf16_f32 v110, v236, v237
	v_cvt_pk_bf16_f32 v111, v238, v239
	v_cvt_pk_bf16_f32 v112, v240, v241
	v_cvt_pk_bf16_f32 v113, v242, v243
	v_cvt_pk_bf16_f32 v114, v244, v245
	v_cvt_pk_bf16_f32 v115, v246, v247
	s_waitcnt lgkmcnt(0)
	s_nop 0
	v_mfma_f32_16x16x32_bf16 v[56:59], v[88:91], v[92:95], v[56:59]
	v_mfma_f32_16x16x32_bf16 v[40:43], v[88:91], v[108:111], v[40:43]
	v_mfma_f32_16x16x32_bf16 v[52:55], v[80:83], v[92:95], v[52:55]
	v_mfma_f32_16x16x32_bf16 v[28:31], v[80:83], v[108:111], v[28:31]
	v_mfma_f32_16x16x32_bf16 v[48:51], v[72:75], v[92:95], v[48:51]
	v_mfma_f32_16x16x32_bf16 v[24:27], v[72:75], v[108:111], v[24:27]
	v_mfma_f32_16x16x32_bf16 v[44:47], v[60:63], v[92:95], v[44:47]
	v_mfma_f32_16x16x32_bf16 v[20:23], v[60:63], v[108:111], v[20:23]
	v_mfma_f32_16x16x32_bf16 v[56:59], v[84:87], v[96:99], v[56:59]
	v_mfma_f32_16x16x32_bf16 v[40:43], v[84:87], v[112:115], v[40:43]
	v_mfma_f32_16x16x32_bf16 v[52:55], v[76:79], v[96:99], v[52:55]
	v_mfma_f32_16x16x32_bf16 v[28:31], v[76:79], v[112:115], v[28:31]
	v_mfma_f32_16x16x32_bf16 v[48:51], v[68:71], v[96:99], v[48:51]
	v_mfma_f32_16x16x32_bf16 v[24:27], v[68:71], v[112:115], v[24:27]
	v_mfma_f32_16x16x32_bf16 v[44:47], v[64:67], v[96:99], v[44:47]
	v_mfma_f32_16x16x32_bf16 v[20:23], v[64:67], v[112:115], v[20:23]
	s_branch .LBB0_2481
.Lsel_c3_s0:
	v_max3_f32 v128, v92, v93, v94
	v_max3_f32 v129, v95, v96, v97
	v_max3_f32 v130, v98, v99, v100
	v_max3_f32 v131, v101, v102, v103
	v_max3_f32 v128, v128, v104, v105
	v_max3_f32 v129, v129, v106, v107
	v_max3_f32 v128, v128, v129, v130
	v_max_f32_e32 v128, v128, v131
	v_mov_b32_e32 v129, v128
	s_nop 1
	v_permlane16_swap_b32_e32 v128, v129
	s_nop 1
	v_max_f32_e32 v128, v128, v129
	v_mov_b32_e32 v129, v128
	s_nop 1
	v_permlane32_swap_b32_e32 v128, v129
	s_nop 1
	v_max_f32_e32 v128, v128, v129
	v_max_f32_e32 v130, 0, v128
	s_nop 0
	v_exp_f32_e64 v128, -v130
	v_add_f32_e32 v124, v124, v130
	v_sub_f32_e32 v92, v92, v130
	v_sub_f32_e32 v93, v93, v130
	v_sub_f32_e32 v94, v94, v130
	v_sub_f32_e32 v95, v95, v130
	v_sub_f32_e32 v96, v96, v130
	v_sub_f32_e32 v97, v97, v130
	v_sub_f32_e32 v98, v98, v130
	v_sub_f32_e32 v99, v99, v130
	v_sub_f32_e32 v100, v100, v130
	v_sub_f32_e32 v101, v101, v130
	v_sub_f32_e32 v102, v102, v130
	v_sub_f32_e32 v103, v103, v130
	v_sub_f32_e32 v104, v104, v130
	v_sub_f32_e32 v105, v105, v130
	v_sub_f32_e32 v106, v106, v130
	v_sub_f32_e32 v107, v107, v130
	v_mul_f32_e32 v127, v127, v128
	v_pk_mul_f32 v[56:57], v[56:57], v[128:129] op_sel_hi:[1,0]
	v_pk_mul_f32 v[58:59], v[58:59], v[128:129] op_sel_hi:[1,0]
	v_pk_mul_f32 v[52:53], v[52:53], v[128:129] op_sel_hi:[1,0]
	v_pk_mul_f32 v[54:55], v[54:55], v[128:129] op_sel_hi:[1,0]
	v_pk_mul_f32 v[48:49], v[48:49], v[128:129] op_sel_hi:[1,0]
	v_pk_mul_f32 v[50:51], v[50:51], v[128:129] op_sel_hi:[1,0]
	v_pk_mul_f32 v[44:45], v[44:45], v[128:129] op_sel_hi:[1,0]
	v_pk_mul_f32 v[46:47], v[46:47], v[128:129] op_sel_hi:[1,0]
	s_branch .Lsel_c3_e0
.Lsel_c3_s1:
	v_max3_f32 v144, v108, v109, v110
	v_max3_f32 v145, v111, v112, v113
	v_max3_f32 v146, v114, v115, v116
	v_max3_f32 v147, v117, v118, v119
	v_max3_f32 v144, v144, v120, v121
	v_max3_f32 v145, v145, v122, v123
	v_max3_f32 v144, v144, v145, v146
	v_max_f32_e32 v144, v144, v147
	v_mov_b32_e32 v145, v144
	s_nop 1
	v_permlane16_swap_b32_e32 v144, v145
	s_nop 1
	v_max_f32_e32 v144, v144, v145
	v_mov_b32_e32 v145, v144
	s_nop 1
	v_permlane32_swap_b32_e32 v144, v145
	s_nop 1
	v_max_f32_e32 v144, v144, v145
	v_max_f32_e32 v147, 0, v144
	s_nop 0
	v_exp_f32_e64 v146, -v147
	v_add_f32_e32 v125, v125, v147
	v_sub_f32_e32 v108, v108, v147
	v_sub_f32_e32 v109, v109, v147
	v_sub_f32_e32 v110, v110, v147
	v_sub_f32_e32 v111, v111, v147
	v_sub_f32_e32 v112, v112, v147
	v_sub_f32_e32 v113, v113, v147
	v_sub_f32_e32 v114, v114, v147
	v_sub_f32_e32 v115, v115, v147
	v_sub_f32_e32 v116, v116, v147
	v_sub_f32_e32 v117, v117, v147
	v_sub_f32_e32 v118, v118, v147
	v_sub_f32_e32 v119, v119, v147
	v_sub_f32_e32 v120, v120, v147
	v_sub_f32_e32 v121, v121, v147
	v_sub_f32_e32 v122, v122, v147
	v_sub_f32_e32 v123, v123, v147
	v_mul_f32_e32 v126, v126, v146
	v_pk_mul_f32 v[40:41], v[40:41], v[146:147] op_sel_hi:[1,0]
	v_pk_mul_f32 v[42:43], v[42:43], v[146:147] op_sel_hi:[1,0]
	v_pk_mul_f32 v[28:29], v[28:29], v[146:147] op_sel_hi:[1,0]
	v_pk_mul_f32 v[30:31], v[30:31], v[146:147] op_sel_hi:[1,0]
	v_pk_mul_f32 v[24:25], v[24:25], v[146:147] op_sel_hi:[1,0]
	v_pk_mul_f32 v[26:27], v[26:27], v[146:147] op_sel_hi:[1,0]
	v_pk_mul_f32 v[20:21], v[20:21], v[146:147] op_sel_hi:[1,0]
	v_pk_mul_f32 v[22:23], v[22:23], v[146:147] op_sel_hi:[1,0]
	s_branch .Lsel_c3_e1

; template <int CGM>
; __device__ __forceinline__ void step_int(const bf16x8 (&kf)[4][2], const bf16x8 (&q)[2][2], float farb, const bool (&selq)[2],
;                                          float (&m)[2], float (&l)[2], f32x4 (&o)[2][4], const unsigned char* Vs, int r, int fq) {
;     f32x4 s[2][4]; float mx[2] = {-1e30f, -1e30f};
; #pragma unroll
;     for (int cg_ = 0; cg_ < 2; ++cg_) if ((CGM >> cg_) & 1) { qk(s[cg_], kf, q[cg_], selq[cg_] ? farb - m[cg_] : -1e30f); mx[cg_] = red_max4(max16v(s[cg_])); }
;     if (__any(mx[0] > 0.f || mx[1] > 0.f)) {
; #pragma unroll
;         for (int cg_ = 0; cg_ < 2; ++cg_) if ((CGM >> cg_) & 1) {
;             const float d = fmaxf(mx[cg_], 0.f), sc = __builtin_amdgcn_exp2f(-d); m[cg_] += d; l[cg_] *= sc;
; #pragma unroll
;             for (int df = 0; df < 4; ++df) o[cg_][df] *= sc;
; #pragma unroll
;             for (int f = 0; f < 4; ++f) s[cg_][f] -= d;
;         }
;     }
;     float p[2][4][4];
; #pragma unroll
;     for (int cg_ = 0; cg_ < 2; ++cg_) if ((CGM >> cg_) & 1) {
;         float rs = 0.f;
; #pragma unroll
;         for (int f = 0; f < 4; ++f)
; #pragma unroll
;             for (int i = 0; i < 4; ++i) { const float pe = __builtin_amdgcn_exp2f(s[cg_][f][i]); p[cg_][f][i] = pe; rs += pe; }
;         l[cg_] += rs;
;     }
;     pv2<CGM>(o, p, Vs, r, fq);
; }
.Lsel_c1_e0:
	v_exp_f32_e32 v232, v92
	v_exp_f32_e32 v233, v93
	v_exp_f32_e32 v234, v94
	v_exp_f32_e32 v235, v95
	v_exp_f32_e32 v236, v96
	v_exp_f32_e32 v237, v97
	v_exp_f32_e32 v238, v98
	v_exp_f32_e32 v239, v99
	ds_read_b128 v[84:87], v142 offset:8192
	ds_read_b128 v[76:79], v142 offset:8704
	ds_read_b128 v[68:71], v142 offset:12288
	ds_read_b128 v[64:67], v142 offset:12800
	v_exp_f32_e32 v240, v100
	v_exp_f32_e32 v241, v101
	v_exp_f32_e32 v242, v102
	v_exp_f32_e32 v243, v103
	v_exp_f32_e32 v244, v104
	v_exp_f32_e32 v245, v105
	v_exp_f32_e32 v246, v106
	v_exp_f32_e32 v247, v107
	v_pk_add_f32 v[130:131], v[232:233], v[234:235]
	v_pk_add_f32 v[130:131], v[130:131], v[236:237]
	v_pk_add_f32 v[130:131], v[130:131], v[238:239]
	v_pk_add_f32 v[130:131], v[130:131], v[240:241]
	v_pk_add_f32 v[130:131], v[130:131], v[242:243]
	v_pk_add_f32 v[130:131], v[130:131], v[244:245]
	v_pk_add_f32 v[130:131], v[130:131], v[246:247]
	v_add_f32_e32 v130, v130, v131
	v_cmp_lt_f32_e32 vcc, 0x42800000, v130
	s_cbranch_vccnz .Lsel_c1_s0
	v_add_f32_e32 v127, v127, v130
	v_cvt_pk_bf16_f32 v92, v232, v233
	v_cvt_pk_bf16_f32 v93, v234, v235
	v_cvt_pk_bf16_f32 v94, v236, v237
	v_cvt_pk_bf16_f32 v95, v238, v239
	v_cvt_pk_bf16_f32 v96, v240, v241
	v_cvt_pk_bf16_f32 v97, v242, v243
	v_cvt_pk_bf16_f32 v98, v244, v245
	v_cvt_pk_bf16_f32 v99, v246, v247
	s_waitcnt lgkmcnt(0)
	s_nop 0
	v_mfma_f32_16x16x32_bf16 v[56:59], v[88:91], v[92:95], v[56:59]
	v_mfma_f32_16x16x32_bf16 v[52:55], v[80:83], v[92:95], v[52:55]
	v_mfma_f32_16x16x32_bf16 v[48:51], v[72:75], v[92:95], v[48:51]
	v_mfma_f32_16x16x32_bf16 v[44:47], v[60:63], v[92:95], v[44:47]
	v_mfma_f32_16x16x32_bf16 v[56:59], v[84:87], v[96:99], v[56:59]
	v_mfma_f32_16x16x32_bf16 v[52:55], v[76:79], v[96:99], v[52:55]
	v_mfma_f32_16x16x32_bf16 v[48:51], v[68:71], v[96:99], v[48:51]
	v_mfma_f32_16x16x32_bf16 v[44:47], v[64:67], v[96:99], v[44:47]
	s_branch .LBB0_2481

; template <int CGM>
; __device__ __forceinline__ void step_int(const bf16x8 (&kf)[4][2], const bf16x8 (&q)[2][2], float farb, const bool (&selq)[2],
;                                          float (&m)[2], float (&l)[2], f32x4 (&o)[2][4], const unsigned char* Vs, int r, int fq) {
;     f32x4 s[2][4]; float mx[2] = {-1e30f, -1e30f};
; #pragma unroll
;     for (int cg_ = 0; cg_ < 2; ++cg_) if ((CGM >> cg_) & 1) { qk(s[cg_], kf, q[cg_], selq[cg_] ? farb - m[cg_] : -1e30f); mx[cg_] = red_max4(max16v(s[cg_])); }
;     if (__any(mx[0] > 0.f || mx[1] > 0.f)) {
; #pragma unroll
;         for (int cg_ = 0; cg_ < 2; ++cg_) if ((CGM >> cg_) & 1) {
;             const float d = fmaxf(mx[cg_], 0.f), sc = __builtin_amdgcn_exp2f(-d); m[cg_] += d; l[cg_] *= sc;
; #pragma unroll
;             for (int df = 0; df < 4; ++df) o[cg_][df] *= sc;
; #pragma unroll
;             for (int f = 0; f < 4; ++f) s[cg_][f] -= d;
;         }
;     }
;     float p[2][4][4];
; #pragma unroll
;     for (int cg_ = 0; cg_ < 2; ++cg_) if ((CGM >> cg_) & 1) {
;         float rs = 0.f;
; #pragma unroll
;         for (int f = 0; f < 4; ++f)
; #pragma unroll
;             for (int i = 0; i < 4; ++i) { const float pe = __builtin_amdgcn_exp2f(s[cg_][f][i]); p[cg_][f][i] = pe; rs += pe; }
;         l[cg_] += rs;
;     }
;     pv2<CGM>(o, p, Vs, r, fq);
; }
.Lsel_c2_e1:
	v_exp_f32_e32 v232, v108
	v_exp_f32_e32 v233, v109
	v_exp_f32_e32 v234, v110
	v_exp_f32_e32 v235, v111
	v_exp_f32_e32 v236, v112
	v_exp_f32_e32 v237, v113
	v_exp_f32_e32 v238, v114
	v_exp_f32_e32 v239, v115
	ds_read_b128 v[84:87], v142 offset:8192
	ds_read_b128 v[76:79], v142 offset:8704
	ds_read_b128 v[68:71], v142 offset:12288
	ds_read_b128 v[64:67], v142 offset:12800
	v_exp_f32_e32 v240, v116
	v_exp_f32_e32 v241, v117
	v_exp_f32_e32 v242, v118
	v_exp_f32_e32 v243, v119
	v_exp_f32_e32 v244, v120
	v_exp_f32_e32 v245, v121
	v_exp_f32_e32 v246, v122
	v_exp_f32_e32 v247, v123
	v_pk_add_f32 v[146:147], v[232:233], v[234:235]
	v_pk_add_f32 v[146:147], v[146:147], v[236:237]
	v_pk_add_f32 v[146:147], v[146:147], v[238:239]
	v_pk_add_f32 v[146:147], v[146:147], v[240:241]
	v_pk_add_f32 v[146:147], v[146:147], v[242:243]
	v_pk_add_f32 v[146:147], v[146:147], v[244:245]
	v_pk_add_f32 v[146:147], v[146:147], v[246:247]
	v_add_f32_e32 v146, v146, v147
	v_cmp_lt_f32_e32 vcc, 0x42800000, v146
	s_cbranch_vccnz .Lsel_c2_s1
	v_add_f32_e32 v126, v126, v146
	v_cvt_pk_bf16_f32 v108, v232, v233
	v_cvt_pk_bf16_f32 v109, v234, v235
	v_cvt_pk_bf16_f32 v110, v236, v237
	v_cvt_pk_bf16_f32 v111, v238, v239
	v_cvt_pk_bf16_f32 v112, v240, v241
	v_cvt_pk_bf16_f32 v113, v242, v243
	v_cvt_pk_bf16_f32 v114, v244, v245
	v_cvt_pk_bf16_f32 v115, v246, v247
	s_waitcnt lgkmcnt(0)
	s_nop 0
	v_mfma_f32_16x16x32_bf16 v[40:43], v[88:91], v[108:111], v[40:43]
	v_mfma_f32_16x16x32_bf16 v[28:31], v[80:83], v[108:111], v[28:31]
	v_mfma_f32_16x16x32_bf16 v[24:27], v[72:75], v[108:111], v[24:27]
	v_mfma_f32_16x16x32_bf16 v[20:23], v[60:63], v[108:111], v[20:23]
	v_mfma_f32_16x16x32_bf16 v[40:43], v[84:87], v[112:115], v[40:43]
	v_mfma_f32_16x16x32_bf16 v[28:31], v[76:79], v[112:115], v[28:31]
	v_mfma_f32_16x16x32_bf16 v[24:27], v[68:71], v[112:115], v[24:27]
	v_mfma_f32_16x16x32_bf16 v[20:23], v[64:67], v[112:115], v[20:23]
	s_branch .LBB0_2481

; template <int CGM>
; __device__ __forceinline__ void step_int(const bf16x8 (&kf)[4][2], const bf16x8 (&q)[2][2], float farb, const bool (&selq)[2],
;                                          float (&m)[2], float (&l)[2], f32x4 (&o)[2][4], const unsigned char* Vs, int r, int fq) {
;     f32x4 s[2][4]; float mx[2] = {-1e30f, -1e30f};
; #pragma unroll
;     for (int cg_ = 0; cg_ < 2; ++cg_) if ((CGM >> cg_) & 1) { qk(s[cg_], kf, q[cg_], selq[cg_] ? farb - m[cg_] : -1e30f); mx[cg_] = red_max4(max16v(s[cg_])); }
;     if (__any(mx[0] > 0.f || mx[1] > 0.f)) {
; #pragma unroll
;         for (int cg_ = 0; cg_ < 2; ++cg_) if ((CGM >> cg_) & 1) {
;             const float d = fmaxf(mx[cg_], 0.f), sc = __builtin_amdgcn_exp2f(-d); m[cg_] += d; l[cg_] *= sc;
; #pragma unroll
;             for (int df = 0; df < 4; ++df) o[cg_][df] *= sc;
; #pragma unroll
;             for (int f = 0; f < 4; ++f) s[cg_][f] -= d;
;         }
;     }
;     float p[2][4][4];
; #pragma unroll
;     for (int cg_ = 0; cg_ < 2; ++cg_) if ((CGM >> cg_) & 1) {
;         float rs = 0.f;
; #pragma unroll
;         for (int f = 0; f < 4; ++f)
; #pragma unroll
;             for (int i = 0; i < 4; ++i) { const float pe = __builtin_amdgcn_exp2f(s[cg_][f][i]); p[cg_][f][i] = pe; rs += pe; }
;         l[cg_] += rs;
;     }
;     pv2<CGM>(o, p, Vs, r, fq);
; }
.Lwin_int_e0:
	v_exp_f32_e32 v232, v116
	v_exp_f32_e32 v233, v117
	v_exp_f32_e32 v234, v118
	v_exp_f32_e32 v235, v119
	v_exp_f32_e32 v236, v120
	v_exp_f32_e32 v237, v121
	v_exp_f32_e32 v238, v122
	v_exp_f32_e32 v239, v123
	ds_read_b128 v[76:79], v182 offset:8192
	ds_read_b128 v[68:71], v182 offset:8704
	ds_read_b128 v[64:67], v182 offset:12288
	ds_read_b128 v[52:55], v182 offset:12800
	v_exp_f32_e32 v240, v124
	v_exp_f32_e32 v241, v125
	v_exp_f32_e32 v242, v126
	v_exp_f32_e32 v243, v127
	v_exp_f32_e32 v244, v132
	v_exp_f32_e32 v245, v133
	v_exp_f32_e32 v246, v134
	v_exp_f32_e32 v247, v135
	v_pk_add_f32 v[190:191], v[232:233], v[234:235]
	v_pk_add_f32 v[190:191], v[190:191], v[236:237]
	v_pk_add_f32 v[190:191], v[190:191], v[238:239]
	v_pk_add_f32 v[190:191], v[190:191], v[240:241]
	v_pk_add_f32 v[190:191], v[190:191], v[242:243]
	v_pk_add_f32 v[190:191], v[190:191], v[244:245]
	v_pk_add_f32 v[190:191], v[190:191], v[246:247]
	v_add_f32_e32 v190, v190, v191
	v_cmp_lt_f32_e32 vcc, 0x42800000, v190
	s_cbranch_vccnz .Lwin_int_s0
	v_add_f32_e32 v129, v155, v190
	v_cvt_pk_bf16_f32 v116, v232, v233
	v_cvt_pk_bf16_f32 v117, v234, v235
	v_cvt_pk_bf16_f32 v118, v236, v237
	v_cvt_pk_bf16_f32 v119, v238, v239
	v_cvt_pk_bf16_f32 v120, v240, v241
	v_cvt_pk_bf16_f32 v121, v242, v243
	v_cvt_pk_bf16_f32 v122, v244, v245
	v_cvt_pk_bf16_f32 v123, v246, v247
.Lwin_int_e1:
	v_exp_f32_e32 v232, v136
	v_exp_f32_e32 v233, v137
	v_exp_f32_e32 v234, v138
	v_exp_f32_e32 v235, v139
	v_exp_f32_e32 v236, v140
	v_exp_f32_e32 v237, v141
	v_exp_f32_e32 v238, v142
	v_exp_f32_e32 v239, v143
	v_exp_f32_e32 v240, v144
	v_exp_f32_e32 v241, v145
	v_exp_f32_e32 v242, v146
	v_exp_f32_e32 v243, v147
	v_exp_f32_e32 v244, v184
	v_exp_f32_e32 v245, v185
	v_exp_f32_e32 v246, v186
	v_exp_f32_e32 v247, v187
	v_pk_add_f32 v[194:195], v[232:233], v[234:235]
	v_pk_add_f32 v[194:195], v[194:195], v[236:237]
	v_pk_add_f32 v[194:195], v[194:195], v[238:239]
	v_pk_add_f32 v[194:195], v[194:195], v[240:241]
	v_pk_add_f32 v[194:195], v[194:195], v[242:243]
	v_pk_add_f32 v[194:195], v[194:195], v[244:245]
	v_pk_add_f32 v[194:195], v[194:195], v[246:247]
	v_add_f32_e32 v194, v194, v195
	v_cmp_lt_f32_e32 vcc, 0x42800000, v194
	s_cbranch_vccnz .Lwin_int_s1
	v_add_f32_e32 v128, v154, v194
	v_cvt_pk_bf16_f32 v136, v232, v233
	v_cvt_pk_bf16_f32 v137, v234, v235
	v_cvt_pk_bf16_f32 v138, v236, v237
	v_cvt_pk_bf16_f32 v139, v238, v239
	v_cvt_pk_bf16_f32 v140, v240, v241
	v_cvt_pk_bf16_f32 v141, v242, v243
	v_cvt_pk_bf16_f32 v142, v244, v245
	v_cvt_pk_bf16_f32 v143, v246, v247
	v_mov_b64_e32 v[158:159], v[156:157]
	s_waitcnt lgkmcnt(0)
	v_mfma_f32_16x16x32_bf16 v[48:51], v[80:83], v[116:119], v[48:51]
	v_mfma_f32_16x16x32_bf16 v[44:47], v[80:83], v[136:139], v[44:47]
	v_mfma_f32_16x16x32_bf16 v[40:43], v[72:75], v[116:119], v[40:43]
	v_mfma_f32_16x16x32_bf16 v[36:39], v[72:75], v[136:139], v[36:39]
	v_mfma_f32_16x16x32_bf16 v[32:35], v[60:63], v[116:119], v[32:35]
	v_mfma_f32_16x16x32_bf16 v[28:31], v[60:63], v[136:139], v[28:31]
	v_mfma_f32_16x16x32_bf16 v[24:27], v[56:59], v[116:119], v[24:27]
	v_mfma_f32_16x16x32_bf16 v[20:23], v[56:59], v[136:139], v[20:23]
	v_mfma_f32_16x16x32_bf16 v[92:95], v[76:79], v[120:123], v[48:51]
	v_mfma_f32_16x16x32_bf16 v[84:87], v[76:79], v[140:143], v[44:47]
	v_mfma_f32_16x16x32_bf16 v[104:107], v[68:71], v[120:123], v[40:43]
	v_mfma_f32_16x16x32_bf16 v[96:99], v[68:71], v[140:143], v[36:39]
	v_mfma_f32_16x16x32_bf16 v[100:103], v[64:67], v[120:123], v[32:35]
	v_mfma_f32_16x16x32_bf16 v[88:91], v[64:67], v[140:143], v[28:31]
	v_mfma_f32_16x16x32_bf16 v[112:115], v[52:55], v[120:123], v[24:27]
	v_mfma_f32_16x16x32_bf16 v[108:111], v[52:55], v[140:143], v[20:23]
	s_branch .LBB0_2733
; template <int CGM>
; __device__ __forceinline__ void step_int(const bf16x8 (&kf)[4][2], const bf16x8 (&q)[2][2], float farb, const bool (&selq)[2],
;                                          float (&m)[2], float (&l)[2], f32x4 (&o)[2][4], const unsigned char* Vs, int r, int fq) {
;     ...
;     for (int cg_ = 0; cg_ < 2; ++cg_) if ((CGM >> cg_) & 1) { qk(s[cg_], kf, q[cg_], selq[cg_] ? farb - m[cg_] : -1e30f); mx[cg_] = red_max4(max16v(s[cg_])); }
;     if (__any(mx[0] > 0.f || mx[1] > 0.f)) {
; #pragma unroll
;         for (int cg_ = 0; cg_ < 2; ++cg_) if ((CGM >> cg_) & 1) {
;             const float d = fmaxf(mx[cg_], 0.f), sc = __builtin_amdgcn_exp2f(-d); m[cg_] += d; l[cg_] *= sc;
; #pragma unroll
;             for (int df = 0; df < 4; ++df) o[cg_][df] *= sc;
; #pragma unroll
;             for (int f = 0; f < 4; ++f) s[cg_][f] -= d;
;         }
;     }
.Lwin_int_s0:
	v_max3_f32 v188, v116, v117, v118
	v_max3_f32 v189, v119, v120, v121
	v_max3_f32 v190, v122, v123, v124
	v_max3_f32 v191, v125, v126, v127
	v_max3_f32 v188, v188, v132, v133
	v_max3_f32 v189, v189, v134, v135
	v_max3_f32 v188, v188, v189, v190
	v_max_f32_e32 v188, v188, v191
	v_mov_b32_e32 v189, v188
	s_nop 1
	v_permlane16_swap_b32_e32 v188, v189
	s_nop 1
	v_max_f32_e32 v188, v188, v189
	v_mov_b32_e32 v189, v188
	s_nop 1
	v_permlane32_swap_b32_e32 v188, v189
	s_nop 1
	v_max_f32_e32 v188, v188, v189
	v_max_f32_e32 v190, 0, v188
	s_nop 0
	v_exp_f32_e64 v188, -v190
	v_add_f32_e32 v156, v156, v190
	v_sub_f32_e32 v116, v116, v190
	v_sub_f32_e32 v117, v117, v190
	v_sub_f32_e32 v118, v118, v190
	v_sub_f32_e32 v119, v119, v190
	v_sub_f32_e32 v120, v120, v190
	v_sub_f32_e32 v121, v121, v190
	v_sub_f32_e32 v122, v122, v190
	v_sub_f32_e32 v123, v123, v190
	v_sub_f32_e32 v124, v124, v190
	v_sub_f32_e32 v125, v125, v190
	v_sub_f32_e32 v126, v126, v190
	v_sub_f32_e32 v127, v127, v190
	v_sub_f32_e32 v132, v132, v190
	v_sub_f32_e32 v133, v133, v190
	v_sub_f32_e32 v134, v134, v190
	v_sub_f32_e32 v135, v135, v190
	v_mul_f32_e32 v155, v155, v188
	v_pk_mul_f32 v[48:49], v[48:49], v[188:189] op_sel_hi:[1,0]
	v_pk_mul_f32 v[50:51], v[50:51], v[188:189] op_sel_hi:[1,0]
	v_pk_mul_f32 v[40:41], v[40:41], v[188:189] op_sel_hi:[1,0]
	v_pk_mul_f32 v[42:43], v[42:43], v[188:189] op_sel_hi:[1,0]
	v_pk_mul_f32 v[32:33], v[32:33], v[188:189] op_sel_hi:[1,0]
	v_pk_mul_f32 v[34:35], v[34:35], v[188:189] op_sel_hi:[1,0]
	v_pk_mul_f32 v[24:25], v[24:25], v[188:189] op_sel_hi:[1,0]
	v_pk_mul_f32 v[26:27], v[26:27], v[188:189] op_sel_hi:[1,0]
	s_branch .Lwin_int_e0
.Lwin_int_s1:
	v_max3_f32 v192, v136, v137, v138
	v_max3_f32 v193, v139, v140, v141
	v_max3_f32 v194, v142, v143, v144
	v_max3_f32 v195, v145, v146, v147
	v_max3_f32 v192, v192, v184, v185
	v_max3_f32 v193, v193, v186, v187
	v_max3_f32 v192, v192, v193, v194
	v_max_f32_e32 v192, v192, v195
	v_mov_b32_e32 v193, v192
	s_nop 1
	v_permlane16_swap_b32_e32 v192, v193
	s_nop 1
	v_max_f32_e32 v192, v192, v193
	v_mov_b32_e32 v193, v192
	s_nop 1
	v_permlane32_swap_b32_e32 v192, v193
	s_nop 1
	v_max_f32_e32 v192, v192, v193
	v_max_f32_e32 v195, 0, v192
	s_nop 0
	v_exp_f32_e64 v194, -v195
	v_add_f32_e32 v157, v157, v195
	v_sub_f32_e32 v136, v136, v195
	v_sub_f32_e32 v137, v137, v195
	v_sub_f32_e32 v138, v138, v195
	v_sub_f32_e32 v139, v139, v195
	v_sub_f32_e32 v140, v140, v195
	v_sub_f32_e32 v141, v141, v195
	v_sub_f32_e32 v142, v142, v195
	v_sub_f32_e32 v143, v143, v195
	v_sub_f32_e32 v144, v144, v195
	v_sub_f32_e32 v145, v145, v195
	v_sub_f32_e32 v146, v146, v195
	v_sub_f32_e32 v147, v147, v195
	v_sub_f32_e32 v184, v184, v195
	v_sub_f32_e32 v185, v185, v195
	v_sub_f32_e32 v186, v186, v195
	v_sub_f32_e32 v187, v187, v195
	v_mul_f32_e32 v154, v154, v194
	v_pk_mul_f32 v[44:45], v[44:45], v[194:195] op_sel_hi:[1,0]
	v_pk_mul_f32 v[46:47], v[46:47], v[194:195] op_sel_hi:[1,0]
	v_pk_mul_f32 v[36:37], v[36:37], v[194:195] op_sel_hi:[1,0]
	v_pk_mul_f32 v[38:39], v[38:39], v[194:195] op_sel_hi:[1,0]
	v_pk_mul_f32 v[28:29], v[28:29], v[194:195] op_sel_hi:[1,0]
	v_pk_mul_f32 v[30:31], v[30:31], v[194:195] op_sel_hi:[1,0]
	v_pk_mul_f32 v[20:21], v[20:21], v[194:195] op_sel_hi:[1,0]
	v_pk_mul_f32 v[22:23], v[22:23], v[194:195] op_sel_hi:[1,0]
	s_branch .Lwin_int_e1
